# prowait + grid-barrier spin loops without s_sleep (poll back-to-back)
# baseline (speedup 1.0000x reference)
; __device__ __forceinline__ unsigned xb_ld(unsigned* p)              { return __hip_atomic_load(p, __ATOMIC_RELAXED, __HIP_MEMORY_SCOPE_AGENT); }
; __device__ __forceinline__ void xcd_barrier_complete(unsigned* bar, unsigned x, unsigned& nloc, unsigned& nx) {
;     const unsigned G = gridDim.x * gridDim.y * gridDim.z;
;     unsigned sum, cnt, mine, sp = 0u;
;     for (;;) {
;         sum = 0u; cnt = 0u; mine = 0u;
; #pragma unroll
;         for (unsigned j = 0; j < 16; ++j) { const unsigned c = xb_ld(&bar[XB_XCNT(j)]); sum += c; cnt += (c > 0u) ? 1u : 0u; mine = (j == x) ? c : mine; }
;         if (sum == G) break;
;         __builtin_amdgcn_s_sleep(1);
;         if ((++sp & 255u) == 0u) { if (xb_ld(&bar[XB_TMO])) break; if (sp > XB_SPIN_CAP) { atomicAdd(&bar[XB_TMO], 1u); break; } }
;     }
;     nloc = mine > 0u ? mine : 1u; nx = cnt > 0u ? cnt : 1u;
; }
.LBB0_588:
	v_readlane_b32 s18, v252, 50
	v_readlane_b32 s19, v252, 51
	s_mov_b64 s[20:21], -1
	s_nop 3
	global_load_dword v0, v144, s[18:19] sc1
	v_readlane_b32 s18, v252, 52
	v_readlane_b32 s19, v252, 53
	s_nop 4
	global_load_dword v1, v144, s[18:19] sc1
	v_readlane_b32 s18, v252, 54
	v_readlane_b32 s19, v252, 55
	s_waitcnt vmcnt(0)
	v_add_u32_e32 v16, v1, v0
	s_nop 2
	global_load_dword v2, v144, s[18:19] sc1
	v_readlane_b32 s18, v252, 56
	v_readlane_b32 s19, v252, 57
	s_waitcnt vmcnt(0)
	v_add_u32_e32 v16, v16, v2
	s_nop 2
	global_load_dword v3, v144, s[18:19] sc1
	v_readlane_b32 s18, v252, 58
	v_readlane_b32 s19, v252, 59
	s_waitcnt vmcnt(0)
	v_add_u32_e32 v16, v16, v3
	s_nop 2
	global_load_dword v4, v144, s[18:19] sc1
	v_readlane_b32 s18, v252, 60
	v_readlane_b32 s19, v252, 61
	s_waitcnt vmcnt(0)
	v_add_u32_e32 v16, v16, v4
	s_nop 2
	global_load_dword v5, v144, s[18:19] sc1
	v_readlane_b32 s18, v252, 62
	v_readlane_b32 s19, v252, 63
	s_waitcnt vmcnt(0)
	v_add_u32_e32 v16, v16, v5
	s_nop 2
	global_load_dword v6, v144, s[18:19] sc1
	v_readlane_b32 s18, v253, 0
	v_readlane_b32 s19, v253, 1
	s_waitcnt vmcnt(0)
	v_add_u32_e32 v16, v16, v6
	s_nop 2
	global_load_dword v7, v144, s[18:19] sc1
	v_readlane_b32 s18, v253, 2
	v_readlane_b32 s19, v253, 3
	s_waitcnt vmcnt(0)
	v_add_u32_e32 v16, v16, v7
	s_nop 2
	global_load_dword v8, v144, s[18:19] sc1
	v_readlane_b32 s18, v253, 4
	v_readlane_b32 s19, v253, 5
	s_waitcnt vmcnt(0)
	v_add_u32_e32 v16, v16, v8
	s_nop 2
	global_load_dword v9, v144, s[18:19] sc1
	v_readlane_b32 s18, v253, 6
	v_readlane_b32 s19, v253, 7
	s_waitcnt vmcnt(0)
	v_add_u32_e32 v16, v16, v9
	s_nop 2
	global_load_dword v10, v144, s[18:19] sc1
	v_readlane_b32 s18, v253, 8
	v_readlane_b32 s19, v253, 9
	s_waitcnt vmcnt(0)
	v_add_u32_e32 v16, v16, v10
	s_nop 2
	global_load_dword v11, v144, s[18:19] sc1
	v_readlane_b32 s18, v253, 10
	v_readlane_b32 s19, v253, 11
	s_waitcnt vmcnt(0)
	v_add_u32_e32 v16, v16, v11
	s_nop 2
	global_load_dword v12, v144, s[18:19] sc1
	v_readlane_b32 s18, v253, 12
	v_readlane_b32 s19, v253, 13
	s_waitcnt vmcnt(0)
	v_add_u32_e32 v16, v16, v12
	s_nop 2
	global_load_dword v13, v144, s[18:19] sc1
	v_readlane_b32 s18, v253, 14
	v_readlane_b32 s19, v253, 15
	s_waitcnt vmcnt(0)
	v_add_u32_e32 v16, v16, v13
	s_nop 2
	global_load_dword v14, v144, s[18:19] sc1
	v_readlane_b32 s18, v253, 16
	v_readlane_b32 s19, v253, 17
	s_waitcnt vmcnt(0)
	v_add_u32_e32 v16, v16, v14
	s_nop 2
	global_load_dword v15, v144, s[18:19] sc1
	s_mov_b64 s[18:19], -1
	s_waitcnt vmcnt(0)
	v_add_u32_e32 v16, v16, v15
	v_cmp_eq_u32_e32 vcc, s2, v16
	s_cbranch_vccnz .LBB0_587
	s_and_b32 s5, s4, 0xff
	s_cmp_eq_u32 s5, 0
	s_mov_b64 s[26:27], -1
	s_cbranch_scc0 .LBB0_592
	v_readlane_b32 s18, v252, 48
	v_readlane_b32 s19, v252, 49
	s_nop 4
	global_load_dword v16, v144, s[18:19] sc1
	s_waitcnt vmcnt(0)
	v_cmp_eq_u32_e32 vcc, 0, v16
	s_cbranch_vccnz .LBB0_594
	s_mov_b64 s[26:27], 0
	s_mov_b64 s[18:19], -1

.LBB0_607:
	s_and_b32 s4, s2, 0xff
	s_mov_b64 s[40:41], -1
	s_cmp_lg_u32 s4, 0
	s_mov_b64 s[26:27], -1
	s_cbranch_scc1 .LBB0_610
	v_readlane_b32 s4, v252, 48
	v_readlane_b32 s5, v252, 49
	s_nop 4
	global_load_dword v0, v144, s[4:5] sc1
	s_waitcnt vmcnt(0)
	v_cmp_eq_u32_e32 vcc, 0, v0
	s_cbranch_vccnz .LBB0_612
	s_mov_b64 s[26:27], 0
	s_mov_b64 s[42:43], -1

; __global__ void __launch_bounds__(512, 2) mega_fwd(Params pin) {
;     ...
;         if (ph + 1 < pin.ph_hi) { if (ph == 0) cg::this_grid().sync(); else xcd_barrier(xbar); }
.LBB0_646:
	global_load_dword v1, v144, s[18:19] offset:32 sc1
	s_waitcnt vmcnt(0)
	v_and_b32_e32 v1, 0xffff0000, v1
	v_cmp_ne_u32_e32 vcc, v1, v0
	s_or_b64 s[20:21], vcc, s[20:21]
	s_andn2_b64 exec, exec, s[20:21]
	s_cbranch_execnz .LBB0_646
	s_getpc_b64 s[98:99]
